# ssd_out grouped-norm pass with all loads in flight
# speedup vs baseline: 1.0680x; 1.0006x over previous
; __device__ __forceinline__ unsigned cvt_pk_bf16(float lo, float hi) { unsigned r; asm volatile("v_cvt_pk_bf16_f32 %0, %1, %2" : "=v"(r) : "v"(lo), "v"(hi)); return r; }
; __device__ __forceinline__ float bflo(unsigned w) { return __uint_as_float(w << 16); }
; __device__ __forceinline__ float bfhi(unsigned w) { return __uint_as_float(w & 0xffff0000u); }
; __device__ void phase_ssd_out(KP P, int layer, LAS unsigned char* lds) {
;     ...
;         {
;             const float* nw = P->ssd_norm + layer * 1024 + h * 64; f32x4 nwv[4];
; #pragma unroll
;             for (int pt = 0; pt < 4; ++pt) nwv[pt] = *(const f32x4*)(nw + pt * 16 + q * 4);
; #pragma unroll
;             for (int lt = 0; lt < 8; ++lt) { const int l = lt * 16 + r; float t = 0.f;
; #pragma unroll
;                 for (int w = 0; w < 8; ++w) t += red[w * 128 + l];
;                 const float rstd = rsqrtf(t * (1.f / 512.f) + EPS);
;                 bf16_t* zp = zbase + (long)l * PW + q * 4; u32x2 v[4];
; #pragma unroll
;                 for (int pt = 0; pt < 4; ++pt) v[pt] = *(const u32x2*)(zp + pt * 16);
; #pragma unroll
;                 for (int pt = 0; pt < 4; ++pt) { u32x2 o; o.x = cvt_pk_bf16(bflo(v[pt].x) * rstd * nwv[pt][0], bfhi(v[pt].x) * rstd * nwv[pt][1]);
;                     o.y = cvt_pk_bf16(bflo(v[pt].y) * rstd * nwv[pt][2], bfhi(v[pt].y) * rstd * nwv[pt][3]); *(u32x2*)(zp + pt * 16) = o; }
;                 }
;         }
.LBB0_23:
	s_waitcnt lgkmcnt(0)
	s_barrier
	s_load_dwordx2 s[10:11], s[36:37], 0x50
	v_add_u32_e32 v16, v162, v164
	v_mov_b32_e32 v17, 0
	v_lshl_add_u64 v[16:17], v[182:183], 0, v[16:17]
	v_add_co_u32_e32 v18, vcc, 0x22000, v16
	s_nop 1
	v_addc_co_u32_e32 v19, vcc, 0, v17, vcc
	v_add_co_u32_e32 v20, vcc, 0x22000, v18
	s_nop 1
	v_addc_co_u32_e32 v21, vcc, 0, v19, vcc
	v_add_co_u32_e32 v22, vcc, 0x22000, v20
	s_nop 1
	v_addc_co_u32_e32 v23, vcc, 0, v21, vcc
	v_add_co_u32_e32 v24, vcc, 0x22000, v22
	s_nop 1
	v_addc_co_u32_e32 v25, vcc, 0, v23, vcc
	v_add_co_u32_e32 v26, vcc, 0x22000, v24
	s_nop 1
	v_addc_co_u32_e32 v27, vcc, 0, v25, vcc
	v_add_co_u32_e32 v28, vcc, 0x22000, v26
	s_nop 1
	v_addc_co_u32_e32 v29, vcc, 0, v27, vcc
	v_add_co_u32_e32 v30, vcc, 0x22000, v28
	s_nop 1
	v_addc_co_u32_e32 v31, vcc, 0, v29, vcc
	v_lshlrev_b32_e32 v168, 2, v156
	s_waitcnt lgkmcnt(0)
	s_add_u32 s10, s10, s8
	s_addc_u32 s11, s11, s9
	v_lshl_add_u64 v[136:137], v[180:181], 2, s[10:11]
	v_lshl_add_u64 v[136:137], v[136:137], 0, v[168:169]
	global_load_dwordx4 v[12:15], v[136:137], off
	global_load_dwordx4 v[8:11], v[136:137], off offset:64
	global_load_dwordx4 v[4:7], v[136:137], off offset:128
	global_load_dwordx4 v[0:3], v[136:137], off offset:192
	global_load_dwordx2 v[32:33], v[16:17], off offset:2560
	global_load_dwordx2 v[34:35], v[16:17], off offset:2592
	global_load_dwordx2 v[36:37], v[16:17], off offset:2624
	global_load_dwordx2 v[38:39], v[16:17], off offset:2656
	global_load_dwordx2 v[40:41], v[18:19], off offset:2560
	global_load_dwordx2 v[42:43], v[18:19], off offset:2592
	global_load_dwordx2 v[44:45], v[18:19], off offset:2624
	global_load_dwordx2 v[46:47], v[18:19], off offset:2656
	global_load_dwordx2 v[48:49], v[20:21], off offset:2560
	global_load_dwordx2 v[50:51], v[20:21], off offset:2592
	global_load_dwordx2 v[52:53], v[20:21], off offset:2624
	global_load_dwordx2 v[54:55], v[20:21], off offset:2656
	global_load_dwordx2 v[56:57], v[22:23], off offset:2560
	global_load_dwordx2 v[58:59], v[22:23], off offset:2592
	global_load_dwordx2 v[60:61], v[22:23], off offset:2624
	global_load_dwordx2 v[62:63], v[22:23], off offset:2656
	global_load_dwordx2 v[64:65], v[24:25], off offset:2560
	global_load_dwordx2 v[66:67], v[24:25], off offset:2592
	global_load_dwordx2 v[68:69], v[24:25], off offset:2624
	global_load_dwordx2 v[70:71], v[24:25], off offset:2656
	global_load_dwordx2 v[72:73], v[26:27], off offset:2560
	global_load_dwordx2 v[74:75], v[26:27], off offset:2592
	global_load_dwordx2 v[76:77], v[26:27], off offset:2624
	global_load_dwordx2 v[78:79], v[26:27], off offset:2656
	global_load_dwordx2 v[80:81], v[28:29], off offset:2560
	global_load_dwordx2 v[82:83], v[28:29], off offset:2592
	global_load_dwordx2 v[84:85], v[28:29], off offset:2624
	global_load_dwordx2 v[86:87], v[28:29], off offset:2656
	global_load_dwordx2 v[88:89], v[30:31], off offset:2560
	global_load_dwordx2 v[90:91], v[30:31], off offset:2592
	global_load_dwordx2 v[92:93], v[30:31], off offset:2624
	global_load_dwordx2 v[94:95], v[30:31], off offset:2656
	ds_read2st64_b32 v[96:97], v197 offset0:176 offset1:178
	ds_read2st64_b32 v[98:99], v197 offset0:180 offset1:182
	ds_read2st64_b32 v[100:101], v197 offset0:184 offset1:186
	ds_read2st64_b32 v[102:103], v197 offset0:188 offset1:190
	v_add_u32_e32 v138, 64, v197
	ds_read2st64_b32 v[104:105], v138 offset0:176 offset1:178
	ds_read2st64_b32 v[106:107], v138 offset0:180 offset1:182
	ds_read2st64_b32 v[108:109], v138 offset0:184 offset1:186
	ds_read2st64_b32 v[110:111], v138 offset0:188 offset1:190
	v_add_u32_e32 v138, 128, v197
	ds_read2st64_b32 v[112:113], v138 offset0:176 offset1:178
	ds_read2st64_b32 v[114:115], v138 offset0:180 offset1:182
	ds_read2st64_b32 v[116:117], v138 offset0:184 offset1:186
	ds_read2st64_b32 v[118:119], v138 offset0:188 offset1:190
	v_add_u32_e32 v138, 192, v197
	ds_read2st64_b32 v[120:121], v138 offset0:176 offset1:178
	ds_read2st64_b32 v[122:123], v138 offset0:180 offset1:182
	ds_read2st64_b32 v[124:125], v138 offset0:184 offset1:186
	ds_read2st64_b32 v[126:127], v138 offset0:188 offset1:190
	s_waitcnt lgkmcnt(0)
	v_add_f32_e32 v128, 0, v96
	v_add_f32_e32 v128, v128, v97
	v_add_f32_e32 v128, v128, v98
	v_add_f32_e32 v128, v128, v99
	v_add_f32_e32 v128, v128, v100
	v_add_f32_e32 v128, v128, v101
	v_add_f32_e32 v128, v128, v102
	v_add_f32_e32 v128, v128, v103
	v_fmamk_f32 v128, v128, 0x3b000000, v209
	v_rsq_f32_e32 v128, v128
	v_add_f32_e32 v129, 0, v104
	v_add_f32_e32 v129, v129, v105
	v_add_f32_e32 v129, v129, v106
	v_add_f32_e32 v129, v129, v107
	v_add_f32_e32 v129, v129, v108
	v_add_f32_e32 v129, v129, v109
	v_add_f32_e32 v129, v129, v110
	v_add_f32_e32 v129, v129, v111
	v_fmamk_f32 v129, v129, 0x3b000000, v209
	v_rsq_f32_e32 v129, v129
	v_add_f32_e32 v130, 0, v112
	v_add_f32_e32 v130, v130, v113
	v_add_f32_e32 v130, v130, v114
	v_add_f32_e32 v130, v130, v115
	v_add_f32_e32 v130, v130, v116
	v_add_f32_e32 v130, v130, v117
	v_add_f32_e32 v130, v130, v118
	v_add_f32_e32 v130, v130, v119
	v_fmamk_f32 v130, v130, 0x3b000000, v209
	v_rsq_f32_e32 v130, v130
	v_add_f32_e32 v131, 0, v120
	v_add_f32_e32 v131, v131, v121
	v_add_f32_e32 v131, v131, v122
	v_add_f32_e32 v131, v131, v123
	v_add_f32_e32 v131, v131, v124
	v_add_f32_e32 v131, v131, v125
	v_add_f32_e32 v131, v131, v126
	v_add_f32_e32 v131, v131, v127
	v_fmamk_f32 v131, v131, 0x3b000000, v209
	v_rsq_f32_e32 v131, v131
	v_add_u32_e32 v138, 256, v197
	ds_read2st64_b32 v[96:97], v138 offset0:176 offset1:178
	ds_read2st64_b32 v[98:99], v138 offset0:180 offset1:182
	ds_read2st64_b32 v[100:101], v138 offset0:184 offset1:186
	ds_read2st64_b32 v[102:103], v138 offset0:188 offset1:190
	v_add_u32_e32 v138, 320, v197
	ds_read2st64_b32 v[104:105], v138 offset0:176 offset1:178
	ds_read2st64_b32 v[106:107], v138 offset0:180 offset1:182
	ds_read2st64_b32 v[108:109], v138 offset0:184 offset1:186
	ds_read2st64_b32 v[110:111], v138 offset0:188 offset1:190
	v_add_u32_e32 v138, 384, v197
	ds_read2st64_b32 v[112:113], v138 offset0:176 offset1:178
	ds_read2st64_b32 v[114:115], v138 offset0:180 offset1:182
	ds_read2st64_b32 v[116:117], v138 offset0:184 offset1:186
	ds_read2st64_b32 v[118:119], v138 offset0:188 offset1:190
	v_add_u32_e32 v138, 448, v197
	ds_read2st64_b32 v[120:121], v138 offset0:176 offset1:178
	ds_read2st64_b32 v[122:123], v138 offset0:180 offset1:182
	ds_read2st64_b32 v[124:125], v138 offset0:184 offset1:186
	ds_read2st64_b32 v[126:127], v138 offset0:188 offset1:190
	s_waitcnt lgkmcnt(0)
; __device__ __forceinline__ unsigned cvt_pk_bf16(float lo, float hi) { unsigned r; asm volatile("v_cvt_pk_bf16_f32 %0, %1, %2" : "=v"(r) : "v"(lo), "v"(hi)); return r; }
; __device__ __forceinline__ float bflo(unsigned w) { return __uint_as_float(w << 16); }
; __device__ __forceinline__ float bfhi(unsigned w) { return __uint_as_float(w & 0xffff0000u); }
; __device__ void phase_ssd_out(KP P, int layer, LAS unsigned char* lds) {
;     ...
;             for (int lt = 0; lt < 8; ++lt) { const int l = lt * 16 + r; float t = 0.f;
; #pragma unroll
;                 for (int w = 0; w < 8; ++w) t += red[w * 128 + l];
;                 const float rstd = rsqrtf(t * (1.f / 512.f) + EPS);
;                 bf16_t* zp = zbase + (long)l * PW + q * 4; u32x2 v[4];
; #pragma unroll
;                 for (int pt = 0; pt < 4; ++pt) v[pt] = *(const u32x2*)(zp + pt * 16);
; #pragma unroll
;                 for (int pt = 0; pt < 4; ++pt) { u32x2 o; o.x = cvt_pk_bf16(bflo(v[pt].x) * rstd * nwv[pt][0], bfhi(v[pt].x) * rstd * nwv[pt][1]);
;                     o.y = cvt_pk_bf16(bflo(v[pt].y) * rstd * nwv[pt][2], bfhi(v[pt].y) * rstd * nwv[pt][3]); *(u32x2*)(zp + pt * 16) = o; }
;                 }
	v_add_f32_e32 v132, 0, v96
	v_add_f32_e32 v132, v132, v97
	v_add_f32_e32 v132, v132, v98
	v_add_f32_e32 v132, v132, v99
	v_add_f32_e32 v132, v132, v100
	v_add_f32_e32 v132, v132, v101
	v_add_f32_e32 v132, v132, v102
	v_add_f32_e32 v132, v132, v103
	v_fmamk_f32 v132, v132, 0x3b000000, v209
	v_rsq_f32_e32 v132, v132
	v_add_f32_e32 v133, 0, v104
	v_add_f32_e32 v133, v133, v105
	v_add_f32_e32 v133, v133, v106
	v_add_f32_e32 v133, v133, v107
	v_add_f32_e32 v133, v133, v108
	v_add_f32_e32 v133, v133, v109
	v_add_f32_e32 v133, v133, v110
	v_add_f32_e32 v133, v133, v111
	v_fmamk_f32 v133, v133, 0x3b000000, v209
	v_rsq_f32_e32 v133, v133
	v_add_f32_e32 v134, 0, v112
	v_add_f32_e32 v134, v134, v113
	v_add_f32_e32 v134, v134, v114
	v_add_f32_e32 v134, v134, v115
	v_add_f32_e32 v134, v134, v116
	v_add_f32_e32 v134, v134, v117
	v_add_f32_e32 v134, v134, v118
	v_add_f32_e32 v134, v134, v119
	v_fmamk_f32 v134, v134, 0x3b000000, v209
	v_rsq_f32_e32 v134, v134
	v_add_f32_e32 v135, 0, v120
	v_add_f32_e32 v135, v135, v121
	v_add_f32_e32 v135, v135, v122
	v_add_f32_e32 v135, v135, v123
	v_add_f32_e32 v135, v135, v124
	v_add_f32_e32 v135, v135, v125
	v_add_f32_e32 v135, v135, v126
	v_add_f32_e32 v135, v135, v127
	v_fmamk_f32 v135, v135, 0x3b000000, v209
	v_rsq_f32_e32 v135, v135
	s_mov_b32 s10, 0xffff0000
	s_waitcnt vmcnt(28)
	v_lshlrev_b32_e32 v140, 16, v32
	v_and_b32_e32 v141, s10, v32
	v_lshlrev_b32_e32 v142, 16, v33
	v_and_b32_e32 v143, s10, v33
	v_mul_f32_e32 v140, v128, v140
	v_mul_f32_e32 v141, v128, v141
	v_mul_f32_e32 v142, v128, v142
	v_mul_f32_e32 v143, v128, v143
	v_mul_f32_e32 v140, v12, v140
	v_mul_f32_e32 v141, v13, v141
	v_mul_f32_e32 v142, v14, v142
	v_mul_f32_e32 v143, v15, v143
	v_cvt_pk_bf16_f32 v32, v140, v141
	v_cvt_pk_bf16_f32 v33, v142, v143
	global_store_dwordx2 v[16:17], v[32:33], off offset:2560
	v_lshlrev_b32_e32 v140, 16, v34
	v_and_b32_e32 v141, s10, v34
	v_lshlrev_b32_e32 v142, 16, v35
	v_and_b32_e32 v143, s10, v35
	v_mul_f32_e32 v140, v128, v140
	v_mul_f32_e32 v141, v128, v141
	v_mul_f32_e32 v142, v128, v142
	v_mul_f32_e32 v143, v128, v143
	v_mul_f32_e32 v140, v8, v140
	v_mul_f32_e32 v141, v9, v141
	v_mul_f32_e32 v142, v10, v142
	v_mul_f32_e32 v143, v11, v143
	v_cvt_pk_bf16_f32 v34, v140, v141
	v_cvt_pk_bf16_f32 v35, v142, v143
	global_store_dwordx2 v[16:17], v[34:35], off offset:2592
	v_lshlrev_b32_e32 v140, 16, v36
	v_and_b32_e32 v141, s10, v36
	v_lshlrev_b32_e32 v142, 16, v37
	v_and_b32_e32 v143, s10, v37
	v_mul_f32_e32 v140, v128, v140
	v_mul_f32_e32 v141, v128, v141
	v_mul_f32_e32 v142, v128, v142
	v_mul_f32_e32 v143, v128, v143
	v_mul_f32_e32 v140, v4, v140
	v_mul_f32_e32 v141, v5, v141
	v_mul_f32_e32 v142, v6, v142
	v_mul_f32_e32 v143, v7, v143
	v_cvt_pk_bf16_f32 v36, v140, v141
	v_cvt_pk_bf16_f32 v37, v142, v143
	global_store_dwordx2 v[16:17], v[36:37], off offset:2624
	v_lshlrev_b32_e32 v140, 16, v38
	v_and_b32_e32 v141, s10, v38
	v_lshlrev_b32_e32 v142, 16, v39
	v_and_b32_e32 v143, s10, v39
	v_mul_f32_e32 v140, v128, v140
	v_mul_f32_e32 v141, v128, v141
	v_mul_f32_e32 v142, v128, v142
	v_mul_f32_e32 v143, v128, v143
	v_mul_f32_e32 v140, v0, v140
	v_mul_f32_e32 v141, v1, v141
	v_mul_f32_e32 v142, v2, v142
	v_mul_f32_e32 v143, v3, v143
	v_cvt_pk_bf16_f32 v38, v140, v141
	v_cvt_pk_bf16_f32 v39, v142, v143
	global_store_dwordx2 v[16:17], v[38:39], off offset:2656
	s_waitcnt vmcnt(28)
	v_lshlrev_b32_e32 v140, 16, v40
	v_and_b32_e32 v141, s10, v40
	v_lshlrev_b32_e32 v142, 16, v41
	v_and_b32_e32 v143, s10, v41
	v_mul_f32_e32 v140, v129, v140
	v_mul_f32_e32 v141, v129, v141
	v_mul_f32_e32 v142, v129, v142
	v_mul_f32_e32 v143, v129, v143
	v_mul_f32_e32 v140, v12, v140
	v_mul_f32_e32 v141, v13, v141
	v_mul_f32_e32 v142, v14, v142
	v_mul_f32_e32 v143, v15, v143
	v_cvt_pk_bf16_f32 v40, v140, v141
	v_cvt_pk_bf16_f32 v41, v142, v143
	global_store_dwordx2 v[18:19], v[40:41], off offset:2560
	v_lshlrev_b32_e32 v140, 16, v42
	v_and_b32_e32 v141, s10, v42
	v_lshlrev_b32_e32 v142, 16, v43
	v_and_b32_e32 v143, s10, v43
	v_mul_f32_e32 v140, v129, v140
	v_mul_f32_e32 v141, v129, v141
	v_mul_f32_e32 v142, v129, v142
	v_mul_f32_e32 v143, v129, v143
	v_mul_f32_e32 v140, v8, v140
	v_mul_f32_e32 v141, v9, v141
	v_mul_f32_e32 v142, v10, v142
	v_mul_f32_e32 v143, v11, v143
	v_cvt_pk_bf16_f32 v42, v140, v141
	v_cvt_pk_bf16_f32 v43, v142, v143
	global_store_dwordx2 v[18:19], v[42:43], off offset:2592
	v_lshlrev_b32_e32 v140, 16, v44
	v_and_b32_e32 v141, s10, v44
	v_lshlrev_b32_e32 v142, 16, v45
	v_and_b32_e32 v143, s10, v45
	v_mul_f32_e32 v140, v129, v140
	v_mul_f32_e32 v141, v129, v141
	v_mul_f32_e32 v142, v129, v142
	v_mul_f32_e32 v143, v129, v143
	v_mul_f32_e32 v140, v4, v140
	v_mul_f32_e32 v141, v5, v141
	v_mul_f32_e32 v142, v6, v142
	v_mul_f32_e32 v143, v7, v143
	v_cvt_pk_bf16_f32 v44, v140, v141
	v_cvt_pk_bf16_f32 v45, v142, v143
	global_store_dwordx2 v[18:19], v[44:45], off offset:2624
	v_lshlrev_b32_e32 v140, 16, v46
	v_and_b32_e32 v141, s10, v46
	v_lshlrev_b32_e32 v142, 16, v47
	v_and_b32_e32 v143, s10, v47
	v_mul_f32_e32 v140, v129, v140
	v_mul_f32_e32 v141, v129, v141
	v_mul_f32_e32 v142, v129, v142
	v_mul_f32_e32 v143, v129, v143
	v_mul_f32_e32 v140, v0, v140
	v_mul_f32_e32 v141, v1, v141
	v_mul_f32_e32 v142, v2, v142
	v_mul_f32_e32 v143, v3, v143
	v_cvt_pk_bf16_f32 v46, v140, v141
	v_cvt_pk_bf16_f32 v47, v142, v143
	global_store_dwordx2 v[18:19], v[46:47], off offset:2656
	s_waitcnt vmcnt(28)
; __device__ __forceinline__ unsigned cvt_pk_bf16(float lo, float hi) { unsigned r; asm volatile("v_cvt_pk_bf16_f32 %0, %1, %2" : "=v"(r) : "v"(lo), "v"(hi)); return r; }
; __device__ __forceinline__ float bflo(unsigned w) { return __uint_as_float(w << 16); }
; __device__ __forceinline__ float bfhi(unsigned w) { return __uint_as_float(w & 0xffff0000u); }
; __device__ void phase_ssd_out(KP P, int layer, LAS unsigned char* lds) {
;     ...
;             for (int lt = 0; lt < 8; ++lt) { const int l = lt * 16 + r; float t = 0.f;
; #pragma unroll
;                 for (int w = 0; w < 8; ++w) t += red[w * 128 + l];
;                 const float rstd = rsqrtf(t * (1.f / 512.f) + EPS);
;                 bf16_t* zp = zbase + (long)l * PW + q * 4; u32x2 v[4];
; #pragma unroll
;                 for (int pt = 0; pt < 4; ++pt) v[pt] = *(const u32x2*)(zp + pt * 16);
; #pragma unroll
;                 for (int pt = 0; pt < 4; ++pt) { u32x2 o; o.x = cvt_pk_bf16(bflo(v[pt].x) * rstd * nwv[pt][0], bfhi(v[pt].x) * rstd * nwv[pt][1]);
;                     o.y = cvt_pk_bf16(bflo(v[pt].y) * rstd * nwv[pt][2], bfhi(v[pt].y) * rstd * nwv[pt][3]); *(u32x2*)(zp + pt * 16) = o; }
;                 }
	v_lshlrev_b32_e32 v140, 16, v48
	v_and_b32_e32 v141, s10, v48
	v_lshlrev_b32_e32 v142, 16, v49
	v_and_b32_e32 v143, s10, v49
	v_mul_f32_e32 v140, v130, v140
	v_mul_f32_e32 v141, v130, v141
	v_mul_f32_e32 v142, v130, v142
	v_mul_f32_e32 v143, v130, v143
	v_mul_f32_e32 v140, v12, v140
	v_mul_f32_e32 v141, v13, v141
	v_mul_f32_e32 v142, v14, v142
	v_mul_f32_e32 v143, v15, v143
	v_cvt_pk_bf16_f32 v48, v140, v141
	v_cvt_pk_bf16_f32 v49, v142, v143
	global_store_dwordx2 v[20:21], v[48:49], off offset:2560
	v_lshlrev_b32_e32 v140, 16, v50
	v_and_b32_e32 v141, s10, v50
	v_lshlrev_b32_e32 v142, 16, v51
	v_and_b32_e32 v143, s10, v51
	v_mul_f32_e32 v140, v130, v140
	v_mul_f32_e32 v141, v130, v141
	v_mul_f32_e32 v142, v130, v142
	v_mul_f32_e32 v143, v130, v143
	v_mul_f32_e32 v140, v8, v140
	v_mul_f32_e32 v141, v9, v141
	v_mul_f32_e32 v142, v10, v142
	v_mul_f32_e32 v143, v11, v143
	v_cvt_pk_bf16_f32 v50, v140, v141
	v_cvt_pk_bf16_f32 v51, v142, v143
	global_store_dwordx2 v[20:21], v[50:51], off offset:2592
	v_lshlrev_b32_e32 v140, 16, v52
	v_and_b32_e32 v141, s10, v52
	v_lshlrev_b32_e32 v142, 16, v53
	v_and_b32_e32 v143, s10, v53
	v_mul_f32_e32 v140, v130, v140
	v_mul_f32_e32 v141, v130, v141
	v_mul_f32_e32 v142, v130, v142
	v_mul_f32_e32 v143, v130, v143
	v_mul_f32_e32 v140, v4, v140
	v_mul_f32_e32 v141, v5, v141
	v_mul_f32_e32 v142, v6, v142
	v_mul_f32_e32 v143, v7, v143
	v_cvt_pk_bf16_f32 v52, v140, v141
	v_cvt_pk_bf16_f32 v53, v142, v143
	global_store_dwordx2 v[20:21], v[52:53], off offset:2624
	v_lshlrev_b32_e32 v140, 16, v54
	v_and_b32_e32 v141, s10, v54
	v_lshlrev_b32_e32 v142, 16, v55
	v_and_b32_e32 v143, s10, v55
	v_mul_f32_e32 v140, v130, v140
	v_mul_f32_e32 v141, v130, v141
	v_mul_f32_e32 v142, v130, v142
	v_mul_f32_e32 v143, v130, v143
	v_mul_f32_e32 v140, v0, v140
	v_mul_f32_e32 v141, v1, v141
	v_mul_f32_e32 v142, v2, v142
	v_mul_f32_e32 v143, v3, v143
	v_cvt_pk_bf16_f32 v54, v140, v141
	v_cvt_pk_bf16_f32 v55, v142, v143
	global_store_dwordx2 v[20:21], v[54:55], off offset:2656
	s_waitcnt vmcnt(28)
	v_lshlrev_b32_e32 v140, 16, v56
	v_and_b32_e32 v141, s10, v56
	v_lshlrev_b32_e32 v142, 16, v57
	v_and_b32_e32 v143, s10, v57
	v_mul_f32_e32 v140, v131, v140
	v_mul_f32_e32 v141, v131, v141
	v_mul_f32_e32 v142, v131, v142
	v_mul_f32_e32 v143, v131, v143
	v_mul_f32_e32 v140, v12, v140
	v_mul_f32_e32 v141, v13, v141
	v_mul_f32_e32 v142, v14, v142
	v_mul_f32_e32 v143, v15, v143
	v_cvt_pk_bf16_f32 v56, v140, v141
	v_cvt_pk_bf16_f32 v57, v142, v143
	global_store_dwordx2 v[22:23], v[56:57], off offset:2560
	v_lshlrev_b32_e32 v140, 16, v58
	v_and_b32_e32 v141, s10, v58
	v_lshlrev_b32_e32 v142, 16, v59
	v_and_b32_e32 v143, s10, v59
	v_mul_f32_e32 v140, v131, v140
	v_mul_f32_e32 v141, v131, v141
	v_mul_f32_e32 v142, v131, v142
	v_mul_f32_e32 v143, v131, v143
	v_mul_f32_e32 v140, v8, v140
	v_mul_f32_e32 v141, v9, v141
	v_mul_f32_e32 v142, v10, v142
	v_mul_f32_e32 v143, v11, v143
	v_cvt_pk_bf16_f32 v58, v140, v141
	v_cvt_pk_bf16_f32 v59, v142, v143
	global_store_dwordx2 v[22:23], v[58:59], off offset:2592
	v_lshlrev_b32_e32 v140, 16, v60
	v_and_b32_e32 v141, s10, v60
	v_lshlrev_b32_e32 v142, 16, v61
	v_and_b32_e32 v143, s10, v61
	v_mul_f32_e32 v140, v131, v140
	v_mul_f32_e32 v141, v131, v141
	v_mul_f32_e32 v142, v131, v142
	v_mul_f32_e32 v143, v131, v143
	v_mul_f32_e32 v140, v4, v140
	v_mul_f32_e32 v141, v5, v141
	v_mul_f32_e32 v142, v6, v142
	v_mul_f32_e32 v143, v7, v143
	v_cvt_pk_bf16_f32 v60, v140, v141
	v_cvt_pk_bf16_f32 v61, v142, v143
	global_store_dwordx2 v[22:23], v[60:61], off offset:2624
	v_lshlrev_b32_e32 v140, 16, v62
	v_and_b32_e32 v141, s10, v62
	v_lshlrev_b32_e32 v142, 16, v63
	v_and_b32_e32 v143, s10, v63
	v_mul_f32_e32 v140, v131, v140
	v_mul_f32_e32 v141, v131, v141
	v_mul_f32_e32 v142, v131, v142
	v_mul_f32_e32 v143, v131, v143
	v_mul_f32_e32 v140, v0, v140
	v_mul_f32_e32 v141, v1, v141
	v_mul_f32_e32 v142, v2, v142
	v_mul_f32_e32 v143, v3, v143
	v_cvt_pk_bf16_f32 v62, v140, v141
	v_cvt_pk_bf16_f32 v63, v142, v143
	global_store_dwordx2 v[22:23], v[62:63], off offset:2656
	s_waitcnt vmcnt(28)
	v_lshlrev_b32_e32 v140, 16, v64
	v_and_b32_e32 v141, s10, v64
	v_lshlrev_b32_e32 v142, 16, v65
	v_and_b32_e32 v143, s10, v65
	v_mul_f32_e32 v140, v132, v140
	v_mul_f32_e32 v141, v132, v141
	v_mul_f32_e32 v142, v132, v142
	v_mul_f32_e32 v143, v132, v143
	v_mul_f32_e32 v140, v12, v140
	v_mul_f32_e32 v141, v13, v141
	v_mul_f32_e32 v142, v14, v142
	v_mul_f32_e32 v143, v15, v143
	v_cvt_pk_bf16_f32 v64, v140, v141
	v_cvt_pk_bf16_f32 v65, v142, v143
	global_store_dwordx2 v[24:25], v[64:65], off offset:2560
	v_lshlrev_b32_e32 v140, 16, v66
	v_and_b32_e32 v141, s10, v66
	v_lshlrev_b32_e32 v142, 16, v67
	v_and_b32_e32 v143, s10, v67
	v_mul_f32_e32 v140, v132, v140
	v_mul_f32_e32 v141, v132, v141
	v_mul_f32_e32 v142, v132, v142
	v_mul_f32_e32 v143, v132, v143
	v_mul_f32_e32 v140, v8, v140
	v_mul_f32_e32 v141, v9, v141
	v_mul_f32_e32 v142, v10, v142
	v_mul_f32_e32 v143, v11, v143
	v_cvt_pk_bf16_f32 v66, v140, v141
	v_cvt_pk_bf16_f32 v67, v142, v143
	global_store_dwordx2 v[24:25], v[66:67], off offset:2592
	v_lshlrev_b32_e32 v140, 16, v68
	v_and_b32_e32 v141, s10, v68
	v_lshlrev_b32_e32 v142, 16, v69
	v_and_b32_e32 v143, s10, v69
	v_mul_f32_e32 v140, v132, v140
	v_mul_f32_e32 v141, v132, v141
	v_mul_f32_e32 v142, v132, v142
	v_mul_f32_e32 v143, v132, v143
	v_mul_f32_e32 v140, v4, v140
	v_mul_f32_e32 v141, v5, v141
	v_mul_f32_e32 v142, v6, v142
	v_mul_f32_e32 v143, v7, v143
	v_cvt_pk_bf16_f32 v68, v140, v141
	v_cvt_pk_bf16_f32 v69, v142, v143
	global_store_dwordx2 v[24:25], v[68:69], off offset:2624
	v_lshlrev_b32_e32 v140, 16, v70
	v_and_b32_e32 v141, s10, v70
	v_lshlrev_b32_e32 v142, 16, v71
	v_and_b32_e32 v143, s10, v71
	v_mul_f32_e32 v140, v132, v140
	v_mul_f32_e32 v141, v132, v141
	v_mul_f32_e32 v142, v132, v142
	v_mul_f32_e32 v143, v132, v143
	v_mul_f32_e32 v140, v0, v140
	v_mul_f32_e32 v141, v1, v141
	v_mul_f32_e32 v142, v2, v142
	v_mul_f32_e32 v143, v3, v143
	v_cvt_pk_bf16_f32 v70, v140, v141
	v_cvt_pk_bf16_f32 v71, v142, v143
	global_store_dwordx2 v[24:25], v[70:71], off offset:2656
	s_waitcnt vmcnt(28)
; __device__ __forceinline__ unsigned cvt_pk_bf16(float lo, float hi) { unsigned r; asm volatile("v_cvt_pk_bf16_f32 %0, %1, %2" : "=v"(r) : "v"(lo), "v"(hi)); return r; }
; __device__ __forceinline__ float bflo(unsigned w) { return __uint_as_float(w << 16); }
; __device__ __forceinline__ float bfhi(unsigned w) { return __uint_as_float(w & 0xffff0000u); }
; __device__ void phase_ssd_out(KP P, int layer, LAS unsigned char* lds) {
;     ...
;             for (int lt = 0; lt < 8; ++lt) { const int l = lt * 16 + r; float t = 0.f;
; #pragma unroll
;                 for (int w = 0; w < 8; ++w) t += red[w * 128 + l];
;                 const float rstd = rsqrtf(t * (1.f / 512.f) + EPS);
;                 bf16_t* zp = zbase + (long)l * PW + q * 4; u32x2 v[4];
; #pragma unroll
;                 for (int pt = 0; pt < 4; ++pt) v[pt] = *(const u32x2*)(zp + pt * 16);
; #pragma unroll
;                 for (int pt = 0; pt < 4; ++pt) { u32x2 o; o.x = cvt_pk_bf16(bflo(v[pt].x) * rstd * nwv[pt][0], bfhi(v[pt].x) * rstd * nwv[pt][1]);
;                     o.y = cvt_pk_bf16(bflo(v[pt].y) * rstd * nwv[pt][2], bfhi(v[pt].y) * rstd * nwv[pt][3]); *(u32x2*)(zp + pt * 16) = o; }
;                 }
	v_lshlrev_b32_e32 v140, 16, v72
	v_and_b32_e32 v141, s10, v72
	v_lshlrev_b32_e32 v142, 16, v73
	v_and_b32_e32 v143, s10, v73
	v_mul_f32_e32 v140, v133, v140
	v_mul_f32_e32 v141, v133, v141
	v_mul_f32_e32 v142, v133, v142
	v_mul_f32_e32 v143, v133, v143
	v_mul_f32_e32 v140, v12, v140
	v_mul_f32_e32 v141, v13, v141
	v_mul_f32_e32 v142, v14, v142
	v_mul_f32_e32 v143, v15, v143
	v_cvt_pk_bf16_f32 v72, v140, v141
	v_cvt_pk_bf16_f32 v73, v142, v143
	global_store_dwordx2 v[26:27], v[72:73], off offset:2560
	v_lshlrev_b32_e32 v140, 16, v74
	v_and_b32_e32 v141, s10, v74
	v_lshlrev_b32_e32 v142, 16, v75
	v_and_b32_e32 v143, s10, v75
	v_mul_f32_e32 v140, v133, v140
	v_mul_f32_e32 v141, v133, v141
	v_mul_f32_e32 v142, v133, v142
	v_mul_f32_e32 v143, v133, v143
	v_mul_f32_e32 v140, v8, v140
	v_mul_f32_e32 v141, v9, v141
	v_mul_f32_e32 v142, v10, v142
	v_mul_f32_e32 v143, v11, v143
	v_cvt_pk_bf16_f32 v74, v140, v141
	v_cvt_pk_bf16_f32 v75, v142, v143
	global_store_dwordx2 v[26:27], v[74:75], off offset:2592
	v_lshlrev_b32_e32 v140, 16, v76
	v_and_b32_e32 v141, s10, v76
	v_lshlrev_b32_e32 v142, 16, v77
	v_and_b32_e32 v143, s10, v77
	v_mul_f32_e32 v140, v133, v140
	v_mul_f32_e32 v141, v133, v141
	v_mul_f32_e32 v142, v133, v142
	v_mul_f32_e32 v143, v133, v143
	v_mul_f32_e32 v140, v4, v140
	v_mul_f32_e32 v141, v5, v141
	v_mul_f32_e32 v142, v6, v142
	v_mul_f32_e32 v143, v7, v143
	v_cvt_pk_bf16_f32 v76, v140, v141
	v_cvt_pk_bf16_f32 v77, v142, v143
	global_store_dwordx2 v[26:27], v[76:77], off offset:2624
	v_lshlrev_b32_e32 v140, 16, v78
	v_and_b32_e32 v141, s10, v78
	v_lshlrev_b32_e32 v142, 16, v79
	v_and_b32_e32 v143, s10, v79
	v_mul_f32_e32 v140, v133, v140
	v_mul_f32_e32 v141, v133, v141
	v_mul_f32_e32 v142, v133, v142
	v_mul_f32_e32 v143, v133, v143
	v_mul_f32_e32 v140, v0, v140
	v_mul_f32_e32 v141, v1, v141
	v_mul_f32_e32 v142, v2, v142
	v_mul_f32_e32 v143, v3, v143
	v_cvt_pk_bf16_f32 v78, v140, v141
	v_cvt_pk_bf16_f32 v79, v142, v143
	global_store_dwordx2 v[26:27], v[78:79], off offset:2656
	s_waitcnt vmcnt(28)
	v_lshlrev_b32_e32 v140, 16, v80
	v_and_b32_e32 v141, s10, v80
	v_lshlrev_b32_e32 v142, 16, v81
	v_and_b32_e32 v143, s10, v81
	v_mul_f32_e32 v140, v134, v140
	v_mul_f32_e32 v141, v134, v141
	v_mul_f32_e32 v142, v134, v142
	v_mul_f32_e32 v143, v134, v143
	v_mul_f32_e32 v140, v12, v140
	v_mul_f32_e32 v141, v13, v141
	v_mul_f32_e32 v142, v14, v142
	v_mul_f32_e32 v143, v15, v143
	v_cvt_pk_bf16_f32 v80, v140, v141
	v_cvt_pk_bf16_f32 v81, v142, v143
	global_store_dwordx2 v[28:29], v[80:81], off offset:2560
	v_lshlrev_b32_e32 v140, 16, v82
	v_and_b32_e32 v141, s10, v82
	v_lshlrev_b32_e32 v142, 16, v83
	v_and_b32_e32 v143, s10, v83
	v_mul_f32_e32 v140, v134, v140
	v_mul_f32_e32 v141, v134, v141
	v_mul_f32_e32 v142, v134, v142
	v_mul_f32_e32 v143, v134, v143
	v_mul_f32_e32 v140, v8, v140
	v_mul_f32_e32 v141, v9, v141
	v_mul_f32_e32 v142, v10, v142
	v_mul_f32_e32 v143, v11, v143
	v_cvt_pk_bf16_f32 v82, v140, v141
	v_cvt_pk_bf16_f32 v83, v142, v143
	global_store_dwordx2 v[28:29], v[82:83], off offset:2592
	v_lshlrev_b32_e32 v140, 16, v84
	v_and_b32_e32 v141, s10, v84
	v_lshlrev_b32_e32 v142, 16, v85
	v_and_b32_e32 v143, s10, v85
	v_mul_f32_e32 v140, v134, v140
	v_mul_f32_e32 v141, v134, v141
	v_mul_f32_e32 v142, v134, v142
	v_mul_f32_e32 v143, v134, v143
	v_mul_f32_e32 v140, v4, v140
	v_mul_f32_e32 v141, v5, v141
	v_mul_f32_e32 v142, v6, v142
	v_mul_f32_e32 v143, v7, v143
	v_cvt_pk_bf16_f32 v84, v140, v141
	v_cvt_pk_bf16_f32 v85, v142, v143
	global_store_dwordx2 v[28:29], v[84:85], off offset:2624
	v_lshlrev_b32_e32 v140, 16, v86
	v_and_b32_e32 v141, s10, v86
	v_lshlrev_b32_e32 v142, 16, v87
	v_and_b32_e32 v143, s10, v87
	v_mul_f32_e32 v140, v134, v140
	v_mul_f32_e32 v141, v134, v141
	v_mul_f32_e32 v142, v134, v142
	v_mul_f32_e32 v143, v134, v143
	v_mul_f32_e32 v140, v0, v140
	v_mul_f32_e32 v141, v1, v141
	v_mul_f32_e32 v142, v2, v142
	v_mul_f32_e32 v143, v3, v143
	v_cvt_pk_bf16_f32 v86, v140, v141
	v_cvt_pk_bf16_f32 v87, v142, v143
	global_store_dwordx2 v[28:29], v[86:87], off offset:2656
	s_waitcnt vmcnt(28)
	v_lshlrev_b32_e32 v140, 16, v88
	v_and_b32_e32 v141, s10, v88
	v_lshlrev_b32_e32 v142, 16, v89
	v_and_b32_e32 v143, s10, v89
	v_mul_f32_e32 v140, v135, v140
	v_mul_f32_e32 v141, v135, v141
	v_mul_f32_e32 v142, v135, v142
	v_mul_f32_e32 v143, v135, v143
	v_mul_f32_e32 v140, v12, v140
	v_mul_f32_e32 v141, v13, v141
	v_mul_f32_e32 v142, v14, v142
	v_mul_f32_e32 v143, v15, v143
	v_cvt_pk_bf16_f32 v88, v140, v141
	v_cvt_pk_bf16_f32 v89, v142, v143
	global_store_dwordx2 v[30:31], v[88:89], off offset:2560
	v_lshlrev_b32_e32 v140, 16, v90
	v_and_b32_e32 v141, s10, v90
	v_lshlrev_b32_e32 v142, 16, v91
	v_and_b32_e32 v143, s10, v91
	v_mul_f32_e32 v140, v135, v140
	v_mul_f32_e32 v141, v135, v141
	v_mul_f32_e32 v142, v135, v142
	v_mul_f32_e32 v143, v135, v143
	v_mul_f32_e32 v140, v8, v140
	v_mul_f32_e32 v141, v9, v141
	v_mul_f32_e32 v142, v10, v142
	v_mul_f32_e32 v143, v11, v143
	v_cvt_pk_bf16_f32 v90, v140, v141
	v_cvt_pk_bf16_f32 v91, v142, v143
	global_store_dwordx2 v[30:31], v[90:91], off offset:2592
	v_lshlrev_b32_e32 v140, 16, v92
	v_and_b32_e32 v141, s10, v92
	v_lshlrev_b32_e32 v142, 16, v93
	v_and_b32_e32 v143, s10, v93
	v_mul_f32_e32 v140, v135, v140
	v_mul_f32_e32 v141, v135, v141
	v_mul_f32_e32 v142, v135, v142
	v_mul_f32_e32 v143, v135, v143
	v_mul_f32_e32 v140, v4, v140
	v_mul_f32_e32 v141, v5, v141
	v_mul_f32_e32 v142, v6, v142
	v_mul_f32_e32 v143, v7, v143
	v_cvt_pk_bf16_f32 v92, v140, v141
	v_cvt_pk_bf16_f32 v93, v142, v143
	global_store_dwordx2 v[30:31], v[92:93], off offset:2624
	v_lshlrev_b32_e32 v140, 16, v94
	v_and_b32_e32 v141, s10, v94
	v_lshlrev_b32_e32 v142, 16, v95
	v_and_b32_e32 v143, s10, v95
	v_mul_f32_e32 v140, v135, v140
	v_mul_f32_e32 v141, v135, v141
	v_mul_f32_e32 v142, v135, v142
	v_mul_f32_e32 v143, v135, v143
	v_mul_f32_e32 v140, v0, v140
	v_mul_f32_e32 v141, v1, v141
	v_mul_f32_e32 v142, v2, v142
	v_mul_f32_e32 v143, v3, v143
	v_cvt_pk_bf16_f32 v94, v140, v141
	v_cvt_pk_bf16_f32 v95, v142, v143
	global_store_dwordx2 v[30:31], v[94:95], off offset:2656
	s_add_i32 s22, s22, s1
	s_cmpk_gt_i32 s22, 0x1ff
	s_cbranch_scc1 .LBB0_48

; __device__ void phase_scan_sc(KP P, int layer) {
;     ...
;     for (int task = gtid; task < 2048 * 128; task += gthreads) {
;         const int ch = (task & 127) * 8; const long rowS = (long)(task >> 7) * 16; const int tin = (int)(rowS & (SEQ - 1));
;         float w0[8], w1[8], w2[8], hm2[8], hm1[8];
; #pragma unroll
;         for (int j = 0; j < 8; ++j) { w0[j] = w[ch + j]; w1[j] = w[1024 + ch + j]; w2[j] = w[2048 + ch + j]; hm2[j] = 0.f; hm1[j] = 0.f; }
;         if (tin >= 2) { unpack8(*(const u32x4*)(proj + (rowS - 2) * PW + COL_HC + ch), hm2); unpack8(*(const u32x4*)(proj + (rowS - 1) * PW + COL_HC + ch), hm1); }
; #pragma unroll
;         for (int i = 0; i < 16; ++i) { float h0[8], bz[8]; bf16_t* bp = proj + (rowS + i) * PW + COL_BZ + ch;
;             unpack8(__builtin_nontemporal_load((const u32x4*)(proj + (rowS + i) * PW + COL_HC + ch)), h0); unpack8(__builtin_nontemporal_load((const u32x4*)bp), bz);
;             float y[8];
; #pragma unroll
;             for (int j = 0; j < 8; ++j) { y[j] = bz[j] * (w0[j] * hm2[j] + w1[j] * hm1[j] + w2[j] * h0[j]); hm2[j] = hm1[j]; hm1[j] = h0[j]; }
;             *(u32x4*)bp = __builtin_bit_cast(u32x4, pack8(y)); }
.Lfix_loop:
	v_and_b32_e32 v1, 0x7f, v0
	v_lshrrev_b32_e32 v2, 7, v0
	v_lshlrev_b32_e32 v3, 6, v2
	v_lshlrev_b32_e32 v4, 5, v1
	v_lshlrev_b32_e32 v6, 4, v1
	v_mov_b32_e32 v7, 0
	v_lshl_add_u64 v[10:11], s[8:9], 0, v[6:7]
	v_mad_u64_u32 v[10:11], s[40:41], v3, s1, v[10:11]
	v_add_co_u32_e32 v12, vcc, 0x2200, v10
	s_nop 1
	v_addc_co_u32_e32 v13, vcc, 0, v11, vcc
	v_add_co_u32_e32 v14, vcc, 0xffffde00, v10
	s_nop 1
	v_addc_co_u32_e32 v15, vcc, -1, v11, vcc
	v_add_co_u32_e32 v16, vcc, 0xffffbc00, v10
	s_nop 1
	v_addc_co_u32_e32 v17, vcc, -1, v11, vcc
	global_load_dwordx4 v[20:23], v[16:17], off offset:2048
	global_load_dwordx4 v[24:27], v[14:15], off offset:2048
	global_load_dwordx4 v[28:31], v[10:11], off offset:2048
	global_load_dwordx4 v[32:35], v[12:13], off offset:2048
	global_load_dwordx4 v[36:39], v[10:11], off
	global_load_dwordx4 v[40:43], v[12:13], off
	global_load_dwordx4 v[44:47], v4, s[10:11]
	global_load_dwordx4 v[48:51], v4, s[10:11] offset:16
	global_load_dwordx4 v[52:55], v4, s[14:15]
	global_load_dwordx4 v[56:59], v4, s[14:15] offset:16
	global_load_dwordx4 v[60:63], v4, s[16:17]
	global_load_dwordx4 v[64:67], v4, s[16:17] offset:16
	v_and_b32_e32 v5, 0x1fff, v3
	v_cmp_eq_u32_e64 s[40:41], 0, v5
	s_waitcnt vmcnt(0)
	s_nop 1
	v_cndmask_b32_e64 v20, v20, 0, s[40:41]
	v_cndmask_b32_e64 v24, v24, 0, s[40:41]
	v_cndmask_b32_e64 v21, v21, 0, s[40:41]
	v_cndmask_b32_e64 v25, v25, 0, s[40:41]
	v_cndmask_b32_e64 v22, v22, 0, s[40:41]
	v_cndmask_b32_e64 v26, v26, 0, s[40:41]
	v_cndmask_b32_e64 v23, v23, 0, s[40:41]
	v_cndmask_b32_e64 v27, v27, 0, s[40:41]
	v_lshlrev_b32_e32 v68, 16, v20
	v_lshlrev_b32_e32 v69, 16, v24
	v_lshlrev_b32_e32 v70, 16, v28
	v_lshlrev_b32_e32 v71, 16, v32
	v_lshlrev_b32_e32 v72, 16, v36
	v_lshlrev_b32_e32 v73, 16, v40
	v_mul_f32_e32 v74, v44, v68
	v_mul_f32_e32 v75, v44, v69
	v_fmac_f32_e32 v74, v52, v69
	v_fmac_f32_e32 v75, v52, v70
	v_fmac_f32_e32 v74, v60, v70
	v_fmac_f32_e32 v75, v60, v71
	v_mul_f32_e32 v74, v72, v74
	v_mul_f32_e32 v75, v73, v75
	v_and_b32_e32 v76, s13, v20
	v_and_b32_e32 v77, s13, v24
	v_and_b32_e32 v78, s13, v28
	v_and_b32_e32 v79, s13, v32
	v_and_b32_e32 v80, s13, v36
	v_and_b32_e32 v81, s13, v40
	v_mul_f32_e32 v82, v45, v76
	v_mul_f32_e32 v83, v45, v77
	v_fmac_f32_e32 v82, v53, v77
	v_fmac_f32_e32 v83, v53, v78
	v_fmac_f32_e32 v82, v61, v78
	v_fmac_f32_e32 v83, v61, v79
	v_mul_f32_e32 v82, v80, v82
	v_mul_f32_e32 v83, v81, v83
	v_cvt_pk_bf16_f32 v84, v74, v82
	v_cvt_pk_bf16_f32 v88, v75, v83
	v_lshlrev_b32_e32 v68, 16, v21
	v_lshlrev_b32_e32 v69, 16, v25
	v_lshlrev_b32_e32 v70, 16, v29
	v_lshlrev_b32_e32 v71, 16, v33
	v_lshlrev_b32_e32 v72, 16, v37
	v_lshlrev_b32_e32 v73, 16, v41
	v_mul_f32_e32 v74, v46, v68
	v_mul_f32_e32 v75, v46, v69
	v_fmac_f32_e32 v74, v54, v69
	v_fmac_f32_e32 v75, v54, v70
	v_fmac_f32_e32 v74, v62, v70
	v_fmac_f32_e32 v75, v62, v71
	v_mul_f32_e32 v74, v72, v74
	v_mul_f32_e32 v75, v73, v75
	v_and_b32_e32 v76, s13, v21
	v_and_b32_e32 v77, s13, v25
	v_and_b32_e32 v78, s13, v29
	v_and_b32_e32 v79, s13, v33
	v_and_b32_e32 v80, s13, v37
	v_and_b32_e32 v81, s13, v41
	v_mul_f32_e32 v82, v47, v76
	v_mul_f32_e32 v83, v47, v77
	v_fmac_f32_e32 v82, v55, v77
	v_fmac_f32_e32 v83, v55, v78
	v_fmac_f32_e32 v82, v63, v78
	v_fmac_f32_e32 v83, v63, v79
	v_mul_f32_e32 v82, v80, v82
	v_mul_f32_e32 v83, v81, v83
	v_cvt_pk_bf16_f32 v85, v74, v82
	v_cvt_pk_bf16_f32 v89, v75, v83
	v_lshlrev_b32_e32 v68, 16, v22
	v_lshlrev_b32_e32 v69, 16, v26
	v_lshlrev_b32_e32 v70, 16, v30
	v_lshlrev_b32_e32 v71, 16, v34
	v_lshlrev_b32_e32 v72, 16, v38
	v_lshlrev_b32_e32 v73, 16, v42
	v_mul_f32_e32 v74, v48, v68
	v_mul_f32_e32 v75, v48, v69
	v_fmac_f32_e32 v74, v56, v69
	v_fmac_f32_e32 v75, v56, v70
	v_fmac_f32_e32 v74, v64, v70
	v_fmac_f32_e32 v75, v64, v71
	v_mul_f32_e32 v74, v72, v74
	v_mul_f32_e32 v75, v73, v75
	v_and_b32_e32 v76, s13, v22
	v_and_b32_e32 v77, s13, v26
	v_and_b32_e32 v78, s13, v30
	v_and_b32_e32 v79, s13, v34
	v_and_b32_e32 v80, s13, v38
	v_and_b32_e32 v81, s13, v42
	v_mul_f32_e32 v82, v49, v76
	v_mul_f32_e32 v83, v49, v77
	v_fmac_f32_e32 v82, v57, v77
	v_fmac_f32_e32 v83, v57, v78
	v_fmac_f32_e32 v82, v65, v78
	v_fmac_f32_e32 v83, v65, v79
	v_mul_f32_e32 v82, v80, v82
	v_mul_f32_e32 v83, v81, v83
	v_cvt_pk_bf16_f32 v86, v74, v82
	v_cvt_pk_bf16_f32 v90, v75, v83
	v_lshlrev_b32_e32 v68, 16, v23
	v_lshlrev_b32_e32 v69, 16, v27
	v_lshlrev_b32_e32 v70, 16, v31
	v_lshlrev_b32_e32 v71, 16, v35
	v_lshlrev_b32_e32 v72, 16, v39
	v_lshlrev_b32_e32 v73, 16, v43
	v_mul_f32_e32 v74, v50, v68
	v_mul_f32_e32 v75, v50, v69
	v_fmac_f32_e32 v74, v58, v69
	v_fmac_f32_e32 v75, v58, v70
	v_fmac_f32_e32 v74, v66, v70
	v_fmac_f32_e32 v75, v66, v71
	v_mul_f32_e32 v74, v72, v74
	v_mul_f32_e32 v75, v73, v75
	v_and_b32_e32 v76, s13, v23
	v_and_b32_e32 v77, s13, v27
	v_and_b32_e32 v78, s13, v31
	v_and_b32_e32 v79, s13, v35
	v_and_b32_e32 v80, s13, v39
	v_and_b32_e32 v81, s13, v43
	v_mul_f32_e32 v82, v51, v76
	v_mul_f32_e32 v83, v51, v77
	v_fmac_f32_e32 v82, v59, v77
	v_fmac_f32_e32 v83, v59, v78
	v_fmac_f32_e32 v82, v67, v78
	v_fmac_f32_e32 v83, v67, v79
	v_mul_f32_e32 v82, v80, v82
	v_mul_f32_e32 v83, v81, v83
	v_cvt_pk_bf16_f32 v87, v74, v82
	v_cvt_pk_bf16_f32 v91, v75, v83
	global_store_dwordx4 v[10:11], v[84:87], off
	global_store_dwordx4 v[12:13], v[88:91], off
	v_add_u32_e32 v0, s4, v0
	v_cmp_gt_u32_e32 vcc, s3, v0
	s_and_b64 exec, exec, vcc
	s_cbranch_execnz .Lfix_loop
